# prompt attention queue: next item index claimed by thread 0 right after the gate loads in the item epilogue (atomic latency overlaps the epilogue)
# baseline (speedup 1.0000x reference)
; __device__ void diff_item(const Params& p, unsigned char* smem, bool sample, int b, int h, int qb, float lam) {
;     ...
;   if (c == 0 && active) {
;     const u16* grow = p.Gb + (size_t)tok * 2048 + h * 128;
; #pragma unroll
;     for (int t = 0; t < 4; ++t)
; #pragma unroll
;       for (int gq = 0; gq < 4; ++gq) gv[t * 4 + gq] = *reinterpret_cast<const u32x2*>(grow + 32 * t + 8 * gq + 4 * hh);
; __device__ void phaseB(const Params& p, unsigned char* smem, int pass, int item_lo, int item_hi) {
;     ...
;         if (tid == 0) *s_item = atomicAdd(ctr + 1 + queue, 1);
;         __syncthreads();
;         const int j = *s_item;
.LBB0_388:
	s_nop 3
	v_and_b32_e32 v88, 63, v175
	s_lshl_b32 s14, s57, 7
	s_setprio 0
	v_and_b32_e32 v65, 64, v161
	v_xor_b32_e32 v64, 32, v161
	v_add_u32_e32 v65, 64, v65
	v_cmp_lt_i32_e32 vcc, v64, v65
	s_waitcnt vmcnt(0)
	s_cmpk_lt_u32 s56, 0x100
	s_cselect_b64 s[0:1], -1, 0
	v_cndmask_b32_e32 v64, v161, v64, vcc
	v_lshlrev_b32_e32 v99, 2, v64
	ds_bpermute_b32 v89, v99, v181
	s_cmpk_gt_u32 s56, 0xff
	v_lshlrev_b32_e32 v162, 3, v174
	s_waitcnt vmcnt(0) lgkmcnt(0)
	s_barrier
	s_cbranch_scc1 .LBB0_390
	v_lshl_add_u64 v[64:65], v[164:165], 1, s[80:81]
	s_lshl_b32 s6, s14, 1
	v_lshl_add_u64 v[64:65], v[64:65], 0, s[6:7]
	v_lshl_add_u64 v[64:65], v[64:65], 0, v[162:163]
	global_load_dwordx2 v[96:97], v[64:65], off
	global_load_dwordx2 v[94:95], v[64:65], off offset:16
	global_load_dwordx2 v[92:93], v[64:65], off offset:32
	global_load_dwordx2 v[90:91], v[64:65], off offset:48
	global_load_dwordx2 v[86:87], v[64:65], off offset:64
	global_load_dwordx2 v[84:85], v[64:65], off offset:80
	global_load_dwordx2 v[82:83], v[64:65], off offset:96
	global_load_dwordx2 v[80:81], v[64:65], off offset:112
	global_load_dwordx2 v[78:79], v[64:65], off offset:128
	global_load_dwordx2 v[76:77], v[64:65], off offset:144
	global_load_dwordx2 v[74:75], v[64:65], off offset:160
	global_load_dwordx2 v[72:73], v[64:65], off offset:176
	global_load_dwordx2 v[70:71], v[64:65], off offset:192
	global_load_dwordx2 v[68:69], v[64:65], off offset:208
	global_load_dwordx2 v[66:67], v[64:65], off offset:224
	s_nop 0
	global_load_dwordx2 v[64:65], v[64:65], off offset:240
	s_and_saveexec_b64 vcc, s[4:5]
	s_cbranch_execz .Lq_nc
	v_mov_b32_e32 v252, 1
	global_atomic_add v253, v163, v252, s[10:11] offset:4 sc0
.Lq_nc:
	s_mov_b64 exec, vcc
	s_mov_b32 s60, 1
